# EW phase: waves 4-7 start about 0.7 us late so the two waves of a SIMD alternate load-wait and compute instead of contending
# baseline (speedup 1.0000x reference)
; #define LAS __attribute__((address_space(3)))
; __device__ __forceinline__ int fresh_lane() { int t; asm volatile("v_mbcnt_lo_u32_b32 %0, -1, 0\n\tv_mbcnt_hi_u32_b32 %0, -1, %0" : "=v"(t)); return t; }
; __global__ void __launch_bounds__(NWAVES * 64, 2) mk_fwd(Args args) {
;     ...
;         case 3: if (ONLY_CASE >= 0 && ONLY_CASE != 3) break;  F.Z = (bf16_t*)(ws + WS_Z); F.gdn_norm_w = inp[13]; F.mlstm_norm_w = inp[20]; F.gmlp_norm_w = inp[17]; F.ig_bias = inp[18]; F.fg_bias = inp[19]; F.CHS = (float*)(ws + WS_CHS); { LAS float* tab = (LAS float*)(F.lds + 8192); const int tt = F.wave * 64 + fresh_lane();
;                     for (int e = tt; e < 1024; e += NWAVES * 64) { const float inv = __builtin_amdgcn_exp2f(-(float)(e & 15) * 0.8304820237218406f); const float rev = (float)(e >> 4) * inv * 0.15915494309189535f; tab[2 * e] = __builtin_amdgcn_cosf(rev); tab[2 * e + 1] = __builtin_amdgcn_sinf(rev); }
;                     __syncthreads(); }
;                   for (int rg = blockIdx.x; rg < MALL / 16 + 288; rg += F.G) { if (rg < MALL / 16) ew_unit(F, l, rg); else chs_unit(F, l, rg - MALL / 16); } break;
.LBB0_763:
	s_or_b64 exec, exec, s[0:1]
	v_readlane_b32 s0, v252, 2
	v_readlane_b32 s1, v252, 3
	s_andn2_b64 vcc, exec, s[0:1]
	s_waitcnt lgkmcnt(0)
	s_barrier
	s_cbranch_vccnz .LBB0_819
	s_cmp_lt_u32 s64, 0x100
	s_cbranch_scc1 .Lew_nostag
	s_sleep 26
.Lew_nostag:
	v_readlane_b32 s3, v254, 37
	s_lshl_b32 s0, s3, 8
	s_ashr_i32 s1, s0, 31
	s_lshl_b32 s6, s3, 6
	s_ashr_i32 s7, s6, 31
	s_lshl_b64 s[8:9], s[0:1], 2
	s_add_u32 s0, s46, s8
	s_addc_u32 s1, s47, s9
	s_lshl_b64 s[6:7], s[6:7], 2
	s_add_u32 s4, s4, s6
	s_addc_u32 s5, s5, s7
	s_add_u32 s10, s40, s8
	s_addc_u32 s11, s41, s9
	s_mov_b32 s3, s72
	s_branch .LBB0_767
